# windowed attention: tiles fully inside the window run a copy of the ALiBi block without compare/select, second element written straight to its destination (4 instead of 7 VALU per element pair); on to
# speedup vs baseline: 1.0021x; 1.0021x over previous
; #define MFMA32(a, b, c) __builtin_amdgcn_mfma_f32_32x32x16_bf16((a), (b), (c), 0, 0, 0)
; template <int MODE>
; DI void attn_item(const Params& p, int layer, int b, int hq, int qb, u16* lds, const int WAVE_S) {
;     ...
;     f32x16 sc[2];
; #pragma unroll
;     for (int k2 = 0; k2 < 2; ++k2) {
; #pragma unroll
;       for (int ks = 0; ks < 4; ++ks) {
;         const bf16x8 kf = *(const bf16x8*)(Ks + (k2 * 32 + r) * LSTR + ks * 16 + h * 8);
;         sc[k2] = (ks == 0) ? MFMA32(kf, qf[0], negm) : MFMA32(kf, qf[ks], sc[k2]);
;       }
;     }
;     if (MODE == 1) {
;       const float tposf = (float)(q0 + r - (kbase0 + t * 64) - 4 * h);
; #pragma unroll
;       for (int k2 = 0; k2 < 2; ++k2)
; #pragma unroll
;         for (int i = 0; i < 16; ++i) {
;           const float dist = fabsf(tposf - (float)(k2 * 32 + (i & 3) + 8 * (i >> 2)));
;           sc[k2][i] = (dist <= 128.f) ? (sc[k2][i] - slope2 * dist) : -1e30f;
;         }
;     }
;     float mx0 = fmaxf(fmaxf(sc[0][0], sc[0][1]), sc[0][2]), mx1 = fmaxf(fmaxf(sc[1][0], sc[1][1]), sc[1][2]);
; #pragma unroll
;     for (int i = 3; i < 15; i += 2) { mx0 = fmaxf(fmaxf(mx0, sc[0][i]), sc[0][i + 1]); mx1 = fmaxf(fmaxf(mx1, sc[1][i]), sc[1][i + 1]); }
;     float mx = fmaxf(fmaxf(mx0, mx1), fmaxf(sc[0][15], sc[1][15]));
.LBB0_184:
	v_max_i32_e32 v50, s85, v116
	v_add_u32_e32 v50, s96, v50
	v_cmp_gt_i32_e32 vcc, s34, v130
	s_and_saveexec_b64 s[18:19], vcc
	s_lshl_b32 s44, s28, 6
	s_add_i32 s44, s44, s84
	v_sub_u32_e32 v50, s44, v130
	s_or_b64 exec, exec, s[18:19]
	s_movk_i32 s18, 0x81
	v_cmp_gt_i32_e32 vcc, s18, v50
	s_and_saveexec_b64 s[44:45], vcc
	s_cbranch_execz .LBB0_180
	s_and_b32 s18, s97, 0x80
	s_mulk_i32 s18, 0x90
	v_add_u32_e32 v133, s18, v131
	ds_read_b128 v[50:53], v133
	ds_read_b128 v[54:57], v133 offset:32
	ds_read_b128 v[134:137], v133 offset:4608
	v_cvt_f32_i32_e32 v128, v132
	s_waitcnt lgkmcnt(2)
	v_mfma_f32_32x32x16_bf16 v[66:81], v[50:53], v[82:85], v[2:17]
	ds_read_b128 v[50:53], v133 offset:64
	s_waitcnt lgkmcnt(2)
	v_mfma_f32_32x32x16_bf16 v[66:81], v[54:57], v[86:89], v[66:81]
	s_waitcnt lgkmcnt(0)
	v_mfma_f32_32x32x16_bf16 v[66:81], v[50:53], v[90:93], v[66:81]
	ds_read_b128 v[50:53], v133 offset:96
	s_waitcnt lgkmcnt(0)
	v_mfma_f32_32x32x16_bf16 v[66:81], v[50:53], v[94:97], v[66:81]
	v_mfma_f32_32x32x16_bf16 v[50:65], v[134:137], v[82:85], v[2:17]
	ds_read_b128 v[134:137], v133 offset:4640
	s_waitcnt lgkmcnt(0)
	v_mfma_f32_32x32x16_bf16 v[50:65], v[134:137], v[86:89], v[50:65]
	ds_read_b128 v[134:137], v133 offset:4672
	s_waitcnt lgkmcnt(0)
	v_mfma_f32_32x32x16_bf16 v[50:65], v[134:137], v[90:93], v[50:65]
	ds_read_b128 v[134:137], v133 offset:4704
	s_waitcnt lgkmcnt(0)
	v_mfma_f32_32x32x16_bf16 v[50:65], v[134:137], v[94:97], v[50:65]
	s_cmp_gt_i32 s101, 0x80
	s_cbranch_scc1 .Lwin_masked
	s_cmp_lt_i32 s100, 0xffffffbb
	s_cbranch_scc1 .Lwin_masked
	v_add_f32_e32 v136, -1.0, v128
	v_fma_f32 v134, -v120, |v128|, v66
	v_fma_f32 v66, -v121, |v136|, v67
	v_mov_b32_e32 v67, v134
	v_pk_add_f32 v[134:135], v[128:129], s[2:3] op_sel_hi:[0,1]
	v_fma_f32 v136, -v120, |v134|, v68
	v_fma_f32 v68, -v121, |v135|, v69
	v_pk_add_f32 v[134:135], v[128:129], s[38:39] op_sel_hi:[0,1]
	v_mov_b32_e32 v69, v136
	v_fma_f32 v136, -v120, |v134|, v70
	v_fma_f32 v70, -v121, |v135|, v71
	v_pk_add_f32 v[134:135], v[128:129], s[4:5] op_sel_hi:[0,1]
	v_mov_b32_e32 v71, v136
	v_fma_f32 v136, -v120, |v134|, v72
	v_fma_f32 v72, -v121, |v135|, v73
	v_pk_add_f32 v[134:135], v[128:129], s[52:53] op_sel_hi:[0,1]
	v_mov_b32_e32 v73, v136
	v_fma_f32 v136, -v120, |v134|, v74
	v_fma_f32 v74, -v121, |v135|, v75
	v_pk_add_f32 v[134:135], v[128:129], s[26:27] op_sel_hi:[0,1]
	v_mov_b32_e32 v75, v136
	v_fma_f32 v136, -v120, |v134|, v76
	v_fma_f32 v76, -v121, |v135|, v77
	v_pk_add_f32 v[134:135], v[128:129], s[76:77] op_sel_hi:[0,1]
	v_mov_b32_e32 v77, v136
	v_fma_f32 v136, -v120, |v134|, v78
	v_fma_f32 v78, -v121, |v135|, v79
	v_pk_add_f32 v[134:135], v[128:129], s[22:23] op_sel_hi:[0,1]
	v_mov_b32_e32 v79, v136
	v_fma_f32 v136, -v120, |v134|, v80
	v_fma_f32 v80, -v121, |v135|, v81
	v_pk_add_f32 v[134:135], v[128:129], s[10:11] op_sel_hi:[0,1]
	v_mov_b32_e32 v81, v136
	v_fma_f32 v136, -v120, |v134|, v50
	v_fma_f32 v50, -v121, |v135|, v51
	v_pk_add_f32 v[134:135], v[128:129], s[30:31] op_sel_hi:[0,1]
	v_mov_b32_e32 v51, v136
	v_fma_f32 v136, -v120, |v134|, v52
	v_fma_f32 v52, -v121, |v135|, v53
	v_pk_add_f32 v[134:135], v[128:129], s[20:21] op_sel_hi:[0,1]
	v_mov_b32_e32 v53, v136
	v_fma_f32 v136, -v120, |v134|, v54
	v_fma_f32 v54, -v121, |v135|, v55
	v_pk_add_f32 v[134:135], v[128:129], s[6:7] op_sel_hi:[0,1]
	v_mov_b32_e32 v55, v136
	v_fma_f32 v136, -v120, |v134|, v56
	v_fma_f32 v56, -v121, |v135|, v57
	v_pk_add_f32 v[134:135], v[128:129], s[42:43] op_sel_hi:[0,1]
	v_mov_b32_e32 v57, v136
	v_fma_f32 v136, -v120, |v134|, v58
	v_fma_f32 v58, -v121, |v135|, v59
	v_pk_add_f32 v[134:135], v[128:129], s[14:15] op_sel_hi:[0,1]
	v_mov_b32_e32 v59, v136
	v_fma_f32 v136, -v120, |v134|, v60
	v_fma_f32 v60, -v121, |v135|, v61
	v_pk_add_f32 v[134:135], v[128:129], s[82:83] op_sel_hi:[0,1]
	v_mov_b32_e32 v61, v136
	v_fma_f32 v136, -v120, |v134|, v62
	v_fma_f32 v62, -v121, |v135|, v63
	v_pk_add_f32 v[134:135], v[128:129], s[8:9] op_sel_hi:[0,1]
	v_mov_b32_e32 v63, v136
	v_fma_f32 v136, -v120, |v134|, v64
	v_fma_f32 v64, -v121, |v135|, v65
	v_max3_f32 v128, v67, v66, v69
	v_max3_f32 v128, v128, v68, v71
	v_max3_f32 v134, v51, v50, v53
	v_max3_f32 v134, v134, v52, v55
	v_max3_f32 v128, v128, v70, v73
	v_max3_f32 v134, v134, v54, v57
	v_max3_f32 v128, v128, v72, v75
	v_max3_f32 v134, v134, v56, v59
	v_max3_f32 v128, v128, v74, v77
	v_max3_f32 v134, v134, v58, v61
	v_mov_b32_e32 v65, v136
	v_max3_f32 v128, v128, v76, v79
	v_max3_f32 v134, v134, v60, v63
	v_max3_f32 v128, v128, v78, v81
	v_max3_f32 v134, v134, v62, v65
	v_max_f32_e32 v135, v80, v64
	v_max3_f32 v128, v128, v134, v135
	v_mov_b32_e32 v134, v128
	s_nop 1
	v_permlane32_swap_b32_e32 v128, v134
	v_max_f32_e32 v134, v134, v134
	v_max_f32_e32 v128, v128, v128
	v_max_f32_e32 v128, v128, v134
	s_branch .Lwin_join
